# attention block epilogue rewritten: bf16 pack first, lane-pair transpose with one DPP move + v_perm_b32 (5 VALU per output dword instead of 9)
# speedup vs baseline: 1.0042x; 1.0005x over previous
; __device__ __forceinline__ unsigned cvt_pk_bf16(float lo, float hi) { const f32x2 v = {lo, hi}; const bf16x2_t b = __builtin_convertvector(v, bf16x2_t); return __builtin_bit_cast(unsigned, b); }
; __device__ __forceinline__ int crow(int r, int hi) { return (r & 3) + 8 * (r >> 2) + 4 * hi; }
; __device__ __forceinline__ void attn_block(const Ptrs& P, int b, int h, int qb, LAS char* lds) {
;     ...
;     if (hi == 0) li_l[r32] = l_reg; asm volatile("s_waitcnt lgkmcnt(0)" ::: "memory");
;     float rli[16];
; #pragma unroll
;     for (int r = 0; r < 16; ++r) rli[r] = __builtin_amdgcn_rcpf(li_l[crow(r, hi)]);
;     const bool odd = (r32 & 1) != 0;
;     bf16* Ow = P.o_() + ((size_t)(b * SEQ + i0 + wid * QBLK + 4 * hi + (odd ? 1 : 0))) * DM + h * DV + (r32 & ~1);
; #pragma unroll
;     for (int r = 0; r < 16; r += 2) { const int rrow = (r & 3) + 8 * (r >> 2);
; #pragma unroll
;         for (int d0 = 0; d0 < 4; ++d0) { const float va = o[d0][r] * rli[r], vb = o[d0][r + 1] * rli[r + 1];
;             const float send = odd ? va : vb;
;             const float recv = __uint_as_float((unsigned)__builtin_amdgcn_update_dpp(0, (int)__float_as_uint(send), 0xB1  , 0xF, 0xF, false));
;             *(unsigned*)(Ow + (size_t)rrow * DM + d0 * 32) = odd ? cvt_pk_bf16(recv, vb) : cvt_pk_bf16(va, recv); } }
.LBB0_611:
	s_or_b64 exec, exec, s[22:23]
	s_waitcnt lgkmcnt(0)
	ds_read_b128 v[68:71], v193
	ds_read_b128 v[72:75], v193 offset:32
	ds_read_b128 v[76:79], v193 offset:64
	ds_read_b128 v[80:83], v193 offset:96
	s_mov_b64 s[22:23], 0
	v_or_b32_e32 v84, s74, v192
	v_add_u32_e32 v84, s6, v84
	v_ashrrev_i32_e32 v85, 31, v84
	v_lshlrev_b64 v[84:85], 12, v[84:85]
	v_lshl_add_u64 v[84:85], v[172:173], 0, v[84:85]
	v_mov_b32_e32 v87, 0x3020706
	v_mov_b32_e32 v88, 0x5040100
	s_nop 0
	v_cndmask_b32_e64 v87, v87, v88, s[4:5]
	s_waitcnt lgkmcnt(0)
	v_rcp_f32_e32 v68, v68
	v_rcp_f32_e32 v69, v69
	v_rcp_f32_e32 v70, v70
	v_rcp_f32_e32 v71, v71
	v_rcp_f32_e32 v72, v72
	v_rcp_f32_e32 v73, v73
	v_rcp_f32_e32 v74, v74
	v_rcp_f32_e32 v75, v75
	v_rcp_f32_e32 v76, v76
	v_rcp_f32_e32 v77, v77
	v_rcp_f32_e32 v78, v78
	v_rcp_f32_e32 v79, v79
	v_rcp_f32_e32 v80, v80
	v_rcp_f32_e32 v81, v81
	v_rcp_f32_e32 v82, v82
	v_rcp_f32_e32 v83, v83
	v_mul_f32_e32 v52, v52, v68
	v_mul_f32_e32 v53, v53, v69
	v_mul_f32_e32 v36, v36, v68
	v_mul_f32_e32 v37, v37, v69
	v_mul_f32_e32 v20, v20, v68
	v_mul_f32_e32 v21, v21, v69
	v_mul_f32_e32 v4, v4, v68
	v_mul_f32_e32 v5, v5, v69
	v_cvt_pk_bf16_f32 v52, v52, v53
	v_cvt_pk_bf16_f32 v36, v36, v37
	v_cvt_pk_bf16_f32 v20, v20, v21
	v_cvt_pk_bf16_f32 v4, v4, v5
	s_nop 0
	v_mov_b32_dpp v53, v52 quad_perm:[1,0,3,2] row_mask:0xf bank_mask:0xf
	v_mov_b32_dpp v37, v36 quad_perm:[1,0,3,2] row_mask:0xf bank_mask:0xf
	v_mov_b32_dpp v21, v20 quad_perm:[1,0,3,2] row_mask:0xf bank_mask:0xf
	v_mov_b32_dpp v5, v4 quad_perm:[1,0,3,2] row_mask:0xf bank_mask:0xf
	v_perm_b32 v52, v53, v52, v87
	v_perm_b32 v36, v37, v36, v87
	v_perm_b32 v20, v21, v20, v87
	v_perm_b32 v4, v5, v4, v87
	global_store_dword v[84:85], v52, off
	global_store_dword v[84:85], v36, off offset:64
	global_store_dword v[84:85], v20, off offset:128
	global_store_dword v[84:85], v4, off offset:192
	v_add_co_u32_e32 v90, vcc, s63, v84
	s_nop 0
	v_addc_co_u32_e32 v91, vcc, 0, v85, vcc
	v_mul_f32_e32 v54, v54, v70
	v_mul_f32_e32 v55, v55, v71
	v_mul_f32_e32 v38, v38, v70
	v_mul_f32_e32 v39, v39, v71
	v_mul_f32_e32 v22, v22, v70
	v_mul_f32_e32 v23, v23, v71
	v_mul_f32_e32 v6, v6, v70
	v_mul_f32_e32 v7, v7, v71
	v_cvt_pk_bf16_f32 v54, v54, v55
	v_cvt_pk_bf16_f32 v38, v38, v39
	v_cvt_pk_bf16_f32 v22, v22, v23
	v_cvt_pk_bf16_f32 v6, v6, v7
	s_nop 0
	v_mov_b32_dpp v55, v54 quad_perm:[1,0,3,2] row_mask:0xf bank_mask:0xf
	v_mov_b32_dpp v39, v38 quad_perm:[1,0,3,2] row_mask:0xf bank_mask:0xf
	v_mov_b32_dpp v23, v22 quad_perm:[1,0,3,2] row_mask:0xf bank_mask:0xf
	v_mov_b32_dpp v7, v6 quad_perm:[1,0,3,2] row_mask:0xf bank_mask:0xf
	v_perm_b32 v54, v55, v54, v87
	v_perm_b32 v38, v39, v38, v87
	v_perm_b32 v22, v23, v22, v87
	v_perm_b32 v6, v7, v6, v87
	global_store_dword v[90:91], v54, off
	global_store_dword v[90:91], v38, off offset:64
	global_store_dword v[90:91], v22, off offset:128
	global_store_dword v[90:91], v6, off offset:192
	v_add_co_u32_e32 v90, vcc, s61, v84
	s_nop 0
	v_addc_co_u32_e32 v91, vcc, 0, v85, vcc
	v_mul_f32_e32 v56, v56, v72
	v_mul_f32_e32 v57, v57, v73
	v_mul_f32_e32 v40, v40, v72
	v_mul_f32_e32 v41, v41, v73
	v_mul_f32_e32 v24, v24, v72
	v_mul_f32_e32 v25, v25, v73
	v_mul_f32_e32 v8, v8, v72
	v_mul_f32_e32 v9, v9, v73
	v_cvt_pk_bf16_f32 v56, v56, v57
	v_cvt_pk_bf16_f32 v40, v40, v41
	v_cvt_pk_bf16_f32 v24, v24, v25
	v_cvt_pk_bf16_f32 v8, v8, v9
	s_nop 0
	v_mov_b32_dpp v57, v56 quad_perm:[1,0,3,2] row_mask:0xf bank_mask:0xf
	v_mov_b32_dpp v41, v40 quad_perm:[1,0,3,2] row_mask:0xf bank_mask:0xf
	v_mov_b32_dpp v25, v24 quad_perm:[1,0,3,2] row_mask:0xf bank_mask:0xf
	v_mov_b32_dpp v9, v8 quad_perm:[1,0,3,2] row_mask:0xf bank_mask:0xf
	v_perm_b32 v56, v57, v56, v87
	v_perm_b32 v40, v41, v40, v87
	v_perm_b32 v24, v25, v24, v87
	v_perm_b32 v8, v9, v8, v87
	global_store_dword v[90:91], v56, off
	global_store_dword v[90:91], v40, off offset:64
	global_store_dword v[90:91], v24, off offset:128
	global_store_dword v[90:91], v8, off offset:192
	v_add_co_u32_e32 v90, vcc, s66, v84
	s_nop 0
	v_addc_co_u32_e32 v91, vcc, 0, v85, vcc
	v_mul_f32_e32 v58, v58, v74
	v_mul_f32_e32 v59, v59, v75
	v_mul_f32_e32 v42, v42, v74
	v_mul_f32_e32 v43, v43, v75
	v_mul_f32_e32 v26, v26, v74
	v_mul_f32_e32 v27, v27, v75
	v_mul_f32_e32 v10, v10, v74
	v_mul_f32_e32 v11, v11, v75
	v_cvt_pk_bf16_f32 v58, v58, v59
	v_cvt_pk_bf16_f32 v42, v42, v43
	v_cvt_pk_bf16_f32 v26, v26, v27
	v_cvt_pk_bf16_f32 v10, v10, v11
	s_nop 0
	v_mov_b32_dpp v59, v58 quad_perm:[1,0,3,2] row_mask:0xf bank_mask:0xf
	v_mov_b32_dpp v43, v42 quad_perm:[1,0,3,2] row_mask:0xf bank_mask:0xf
	v_mov_b32_dpp v27, v26 quad_perm:[1,0,3,2] row_mask:0xf bank_mask:0xf
; __device__ __forceinline__ unsigned cvt_pk_bf16(float lo, float hi) { const f32x2 v = {lo, hi}; const bf16x2_t b = __builtin_convertvector(v, bf16x2_t); return __builtin_bit_cast(unsigned, b); }
; __device__ __forceinline__ void attn_block(const Ptrs& P, int b, int h, int qb, LAS char* lds) {
;     ...
;     for (int r = 0; r < 16; r += 2) { const int rrow = (r & 3) + 8 * (r >> 2);
; #pragma unroll
;         for (int d0 = 0; d0 < 4; ++d0) { const float va = o[d0][r] * rli[r], vb = o[d0][r + 1] * rli[r + 1];
;             const float send = odd ? va : vb;
;             const float recv = __uint_as_float((unsigned)__builtin_amdgcn_update_dpp(0, (int)__float_as_uint(send), 0xB1  , 0xF, 0xF, false));
;             *(unsigned*)(Ow + (size_t)rrow * DM + d0 * 32) = odd ? cvt_pk_bf16(recv, vb) : cvt_pk_bf16(va, recv); } }
;     __syncthreads();
	v_mov_b32_dpp v11, v10 quad_perm:[1,0,3,2] row_mask:0xf bank_mask:0xf
	v_perm_b32 v58, v59, v58, v87
	v_perm_b32 v42, v43, v42, v87
	v_perm_b32 v26, v27, v26, v87
	v_perm_b32 v10, v11, v10, v87
	global_store_dword v[90:91], v58, off
	global_store_dword v[90:91], v42, off offset:64
	global_store_dword v[90:91], v26, off offset:128
	global_store_dword v[90:91], v10, off offset:192
	v_add_co_u32_e32 v90, vcc, s69, v84
	s_nop 0
	v_addc_co_u32_e32 v91, vcc, 0, v85, vcc
	v_mul_f32_e32 v60, v60, v76
	v_mul_f32_e32 v61, v61, v77
	v_mul_f32_e32 v44, v44, v76
	v_mul_f32_e32 v45, v45, v77
	v_mul_f32_e32 v28, v28, v76
	v_mul_f32_e32 v29, v29, v77
	v_mul_f32_e32 v12, v12, v76
	v_mul_f32_e32 v13, v13, v77
	v_cvt_pk_bf16_f32 v60, v60, v61
	v_cvt_pk_bf16_f32 v44, v44, v45
	v_cvt_pk_bf16_f32 v28, v28, v29
	v_cvt_pk_bf16_f32 v12, v12, v13
	s_nop 0
	v_mov_b32_dpp v61, v60 quad_perm:[1,0,3,2] row_mask:0xf bank_mask:0xf
	v_mov_b32_dpp v45, v44 quad_perm:[1,0,3,2] row_mask:0xf bank_mask:0xf
	v_mov_b32_dpp v29, v28 quad_perm:[1,0,3,2] row_mask:0xf bank_mask:0xf
	v_mov_b32_dpp v13, v12 quad_perm:[1,0,3,2] row_mask:0xf bank_mask:0xf
	v_perm_b32 v60, v61, v60, v87
	v_perm_b32 v44, v45, v44, v87
	v_perm_b32 v28, v29, v28, v87
	v_perm_b32 v12, v13, v12, v87
	global_store_dword v[90:91], v60, off
	global_store_dword v[90:91], v44, off offset:64
	global_store_dword v[90:91], v28, off offset:128
	global_store_dword v[90:91], v12, off offset:192
	v_add_co_u32_e32 v90, vcc, s70, v84
	s_nop 0
	v_addc_co_u32_e32 v91, vcc, 0, v85, vcc
	v_mul_f32_e32 v62, v62, v78
	v_mul_f32_e32 v63, v63, v79
	v_mul_f32_e32 v46, v46, v78
	v_mul_f32_e32 v47, v47, v79
	v_mul_f32_e32 v30, v30, v78
	v_mul_f32_e32 v31, v31, v79
	v_mul_f32_e32 v14, v14, v78
	v_mul_f32_e32 v15, v15, v79
	v_cvt_pk_bf16_f32 v62, v62, v63
	v_cvt_pk_bf16_f32 v46, v46, v47
	v_cvt_pk_bf16_f32 v30, v30, v31
	v_cvt_pk_bf16_f32 v14, v14, v15
	s_nop 0
	v_mov_b32_dpp v63, v62 quad_perm:[1,0,3,2] row_mask:0xf bank_mask:0xf
	v_mov_b32_dpp v47, v46 quad_perm:[1,0,3,2] row_mask:0xf bank_mask:0xf
	v_mov_b32_dpp v31, v30 quad_perm:[1,0,3,2] row_mask:0xf bank_mask:0xf
	v_mov_b32_dpp v15, v14 quad_perm:[1,0,3,2] row_mask:0xf bank_mask:0xf
	v_perm_b32 v62, v63, v62, v87
	v_perm_b32 v46, v47, v46, v87
	v_perm_b32 v30, v31, v30, v87
	v_perm_b32 v14, v15, v14, v87
	global_store_dword v[90:91], v62, off
	global_store_dword v[90:91], v46, off offset:64
	global_store_dword v[90:91], v30, off offset:128
	global_store_dword v[90:91], v14, off offset:192
	v_add_co_u32_e32 v90, vcc, s67, v84
	s_nop 0
	v_addc_co_u32_e32 v91, vcc, 0, v85, vcc
	v_mul_f32_e32 v64, v64, v80
	v_mul_f32_e32 v65, v65, v81
	v_mul_f32_e32 v48, v48, v80
	v_mul_f32_e32 v49, v49, v81
	v_mul_f32_e32 v32, v32, v80
	v_mul_f32_e32 v33, v33, v81
	v_mul_f32_e32 v16, v16, v80
	v_mul_f32_e32 v17, v17, v81
	v_cvt_pk_bf16_f32 v64, v64, v65
	v_cvt_pk_bf16_f32 v48, v48, v49
	v_cvt_pk_bf16_f32 v32, v32, v33
	v_cvt_pk_bf16_f32 v16, v16, v17
	s_nop 0
	v_mov_b32_dpp v65, v64 quad_perm:[1,0,3,2] row_mask:0xf bank_mask:0xf
	v_mov_b32_dpp v49, v48 quad_perm:[1,0,3,2] row_mask:0xf bank_mask:0xf
	v_mov_b32_dpp v33, v32 quad_perm:[1,0,3,2] row_mask:0xf bank_mask:0xf
	v_mov_b32_dpp v17, v16 quad_perm:[1,0,3,2] row_mask:0xf bank_mask:0xf
	v_perm_b32 v64, v65, v64, v87
	v_perm_b32 v48, v49, v48, v87
	v_perm_b32 v32, v33, v32, v87
	v_perm_b32 v16, v17, v16, v87
	global_store_dword v[90:91], v64, off
	global_store_dword v[90:91], v48, off offset:64
	global_store_dword v[90:91], v32, off offset:128
	global_store_dword v[90:91], v16, off offset:192
	v_add_co_u32_e32 v90, vcc, s71, v84
	s_nop 0
	v_addc_co_u32_e32 v91, vcc, 0, v85, vcc
	v_mul_f32_e32 v66, v66, v82
	v_mul_f32_e32 v67, v67, v83
	v_mul_f32_e32 v50, v50, v82
	v_mul_f32_e32 v51, v51, v83
	v_mul_f32_e32 v34, v34, v82
	v_mul_f32_e32 v35, v35, v83
	v_mul_f32_e32 v18, v18, v82
	v_mul_f32_e32 v19, v19, v83
	v_cvt_pk_bf16_f32 v66, v66, v67
	v_cvt_pk_bf16_f32 v50, v50, v51
	v_cvt_pk_bf16_f32 v34, v34, v35
	v_cvt_pk_bf16_f32 v18, v18, v19
	s_nop 0
	v_mov_b32_dpp v67, v66 quad_perm:[1,0,3,2] row_mask:0xf bank_mask:0xf
	v_mov_b32_dpp v51, v50 quad_perm:[1,0,3,2] row_mask:0xf bank_mask:0xf
	v_mov_b32_dpp v35, v34 quad_perm:[1,0,3,2] row_mask:0xf bank_mask:0xf
	v_mov_b32_dpp v19, v18 quad_perm:[1,0,3,2] row_mask:0xf bank_mask:0xf
	v_perm_b32 v66, v67, v66, v87
	v_perm_b32 v50, v51, v50, v87
	v_perm_b32 v34, v35, v34, v87
	v_perm_b32 v18, v19, v18, v87
	global_store_dword v[90:91], v66, off
	global_store_dword v[90:91], v50, off offset:64
	global_store_dword v[90:91], v34, off offset:128
	global_store_dword v[90:91], v18, off offset:192
	s_and_b64 vcc, exec, s[36:37]
	s_barrier
	s_cbranch_vccnz .LBB0_609
